# residual-add epilogues (out-projection, down-projection): residual loads and result stores use 4 lanes per 64 contiguous bytes, moved to/from the accumulator lane layout through a per-wave LDS transpo
# speedup vs baseline: 1.0310x; 1.0074x over previous
; __device__ __forceinline__ unsigned cvt_pk_bf16(float lo, float hi) { f32x2_t v = {lo, hi}; bf16x2_t b = __builtin_convertvector(v, bf16x2_t); return __builtin_bit_cast(unsigned, b); }
;     __device__ __forceinline__ void operator()(const f32x4 (&acc)[2][2][4][2], const Unit& u, int wr, int wc, int fr, int fq) const {
;         typedef unsigned u32x2v __attribute__((ext_vector_type(2)));
;         const int row0 = u.pm * BM + wr * 64 + fr, col0 = u.pn * BM + wc * 32 + 4 * fq;
;         u32x2v bs[2][4][2][2];
; #pragma unroll
;         for (int ai = 0; ai < 2; ++ai)
; #pragma unroll
;             for (int m = 0; m < 4; ++m)
; #pragma unroll
;                 for (int bj = 0; bj < 2; ++bj)
; #pragma unroll
;                     for (int n = 0; n < 2; ++n) bs[ai][m][bj][n] = *(const u32x2v*)(hb + (size_t)(row0 + ai * HALF + m * 16) * 1024 + col0 + bj * HALF + n * 16);
; #pragma unroll
;         for (int ai = 0; ai < 2; ++ai)
; #pragma unroll
;             for (int m = 0; m < 4; ++m) { const int row = row0 + ai * HALF + m * 16; const size_t off = (size_t)row * 1024 + col0; float q = 0.f;
; #pragma unroll
;                 for (int bj = 0; bj < 2; ++bj)
; #pragma unroll
;                     for (int n = 0; n < 2; ++n) { const size_t o2 = off + bj * HALF + n * 16; const u32x2v b = bs[ai][m][bj][n];
;                         const f32x4 bf = {__builtin_bit_cast(float, b.x << 16), __builtin_bit_cast(float, b.x & 0xffff0000u), __builtin_bit_cast(float, b.y << 16), __builtin_bit_cast(float, b.y & 0xffff0000u)};
;                         const f32x4 o = bf + acc[ai][bj][m][n];
;                         u32x2v w; w.x = cvt_pk_bf16(o[0], o[1]); w.y = cvt_pk_bf16(o[2], o[3]); *(u32x2v*)(hb + o2) = w;
.LBB0_523:
	s_lshl_b32 s6, s24, 8
	s_add_i32 s6, s6, s16
	v_lshrrev_b32_e32 v136, 2, v242
	v_add_u32_e32 v136, s6, v136
	v_and_b32_e32 v138, 0x60, v230
	v_lshl_or_b32 v138, s23, 8, v138
	v_lshlrev_b32_e32 v138, 1, v138
	v_and_b32_e32 v139, 3, v242
	v_lshl_or_b32 v138, v139, 4, v138
	v_lshl_or_b32 v140, v136, 11, v138
	v_mov_b32_e32 v141, 0
	v_lshl_add_u64 v[212:213], s[84:85], 0, v[140:141]
	s_mov_b64 s[6:7], 0x8000
	v_lshl_add_u64 v[214:215], v[212:213], 0, s[6:7]
	s_mov_b64 s[6:7], 0x10000
	v_lshl_add_u64 v[216:217], v[212:213], 0, s[6:7]
	s_mov_b64 s[6:7], 0x18000
	v_lshl_add_u64 v[218:219], v[212:213], 0, s[6:7]
	s_mov_b64 s[6:7], 0x40000
	v_lshl_add_u64 v[220:221], v[212:213], 0, s[6:7]
	s_mov_b64 s[6:7], 0x48000
	v_lshl_add_u64 v[222:223], v[212:213], 0, s[6:7]
	s_mov_b64 s[6:7], 0x50000
	v_lshl_add_u64 v[224:225], v[212:213], 0, s[6:7]
	s_mov_b64 s[6:7], 0x58000
	v_lshl_add_u64 v[226:227], v[212:213], 0, s[6:7]
	global_load_dwordx4 v[144:147], v[212:213], off
	global_load_dwordx4 v[148:151], v[212:213], off offset:256
	global_load_dwordx4 v[152:155], v[214:215], off
	global_load_dwordx4 v[156:159], v[214:215], off offset:256
	global_load_dwordx4 v[160:163], v[216:217], off
	global_load_dwordx4 v[168:171], v[216:217], off offset:256
	global_load_dwordx4 v[172:175], v[218:219], off
	global_load_dwordx4 v[176:179], v[218:219], off offset:256
	global_load_dwordx4 v[180:183], v[220:221], off
	global_load_dwordx4 v[184:187], v[220:221], off offset:256
	global_load_dwordx4 v[188:191], v[222:223], off
	global_load_dwordx4 v[192:195], v[222:223], off offset:256
	global_load_dwordx4 v[196:199], v[224:225], off
	global_load_dwordx4 v[200:203], v[224:225], off offset:256
	global_load_dwordx4 v[204:207], v[226:227], off
	global_load_dwordx4 v[208:211], v[226:227], off offset:256
	v_lshrrev_b32_e32 v136, 2, v242
	v_and_b32_e32 v137, 3, v242
	v_lshrrev_b32_e32 v138, 2, v136
	v_xor_b32_e32 v137, v137, v138
	v_lshlrev_b32_e32 v137, 4, v137
	v_lshl_or_b32 v234, v136, 6, v137
	v_bfe_u32 v136, v230, 2, 1
	v_bfe_u32 v137, v230, 3, 1
	v_lshl_or_b32 v136, v136, 1, v137
	v_lshrrev_b32_e32 v137, 2, v228
	v_xor_b32_e32 v136, v136, v137
	v_lshlrev_b32_e32 v136, 4, v136
	v_lshl_or_b32 v235, v228, 6, v136
	s_lshl_b32 s6, s12, 10
	s_lshl_b32 s7, s16, 6
	s_add_i32 s6, s6, s7
	s_add_i32 s6, s6, 0x23000
	v_add_u32_e32 v234, s6, v234
	v_add_u32_e32 v235, s6, v235
	v_permlane16_swap_b32_e32 v126, v122
	v_permlane16_swap_b32_e32 v127, v123
	v_permlane16_swap_b32_e32 v128, v124
	v_permlane16_swap_b32_e32 v129, v125
	v_permlane16_swap_b32_e32 v118, v114
	v_permlane16_swap_b32_e32 v119, v115
	v_permlane16_swap_b32_e32 v120, v116
	v_permlane16_swap_b32_e32 v121, v117
	v_permlane16_swap_b32_e32 v110, v106
	v_permlane16_swap_b32_e32 v111, v107
	v_permlane16_swap_b32_e32 v112, v108
	v_permlane16_swap_b32_e32 v113, v109
	v_permlane16_swap_b32_e32 v102, v98
	v_permlane16_swap_b32_e32 v103, v99
	v_permlane16_swap_b32_e32 v104, v100
	v_permlane16_swap_b32_e32 v105, v101
	v_permlane16_swap_b32_e32 v94, v90
	v_permlane16_swap_b32_e32 v95, v91
	v_permlane16_swap_b32_e32 v96, v92
	v_permlane16_swap_b32_e32 v97, v93
	v_permlane16_swap_b32_e32 v86, v82
	v_permlane16_swap_b32_e32 v87, v83
	v_permlane16_swap_b32_e32 v88, v84
	v_permlane16_swap_b32_e32 v89, v85
	v_permlane16_swap_b32_e32 v78, v74
	v_permlane16_swap_b32_e32 v79, v75
	v_permlane16_swap_b32_e32 v80, v76
	v_permlane16_swap_b32_e32 v81, v77
	v_permlane16_swap_b32_e32 v70, v66
	v_permlane16_swap_b32_e32 v71, v67
	v_permlane16_swap_b32_e32 v72, v68
	v_permlane16_swap_b32_e32 v73, v69
	v_permlane16_swap_b32_e32 v62, v58
	v_permlane16_swap_b32_e32 v63, v59
	v_permlane16_swap_b32_e32 v64, v60
	v_permlane16_swap_b32_e32 v65, v61
	v_permlane16_swap_b32_e32 v54, v50
	v_permlane16_swap_b32_e32 v55, v51
	v_permlane16_swap_b32_e32 v56, v52
	v_permlane16_swap_b32_e32 v57, v53
	v_permlane16_swap_b32_e32 v46, v42
	v_permlane16_swap_b32_e32 v47, v43
	v_permlane16_swap_b32_e32 v48, v44
	v_permlane16_swap_b32_e32 v49, v45
	v_permlane16_swap_b32_e32 v38, v34
	v_permlane16_swap_b32_e32 v39, v35
	v_permlane16_swap_b32_e32 v40, v36
	v_permlane16_swap_b32_e32 v41, v37
	v_permlane16_swap_b32_e32 v30, v26
	v_permlane16_swap_b32_e32 v31, v27
	v_permlane16_swap_b32_e32 v32, v28
	v_permlane16_swap_b32_e32 v33, v29
	v_permlane16_swap_b32_e32 v22, v18
	v_permlane16_swap_b32_e32 v23, v19
	v_permlane16_swap_b32_e32 v24, v20
	v_permlane16_swap_b32_e32 v25, v21
	v_permlane16_swap_b32_e32 v14, v10
	v_permlane16_swap_b32_e32 v15, v11
	v_permlane16_swap_b32_e32 v16, v12
	v_permlane16_swap_b32_e32 v17, v13
	v_permlane16_swap_b32_e32 v6, v2
	v_permlane16_swap_b32_e32 v7, v3
	v_permlane16_swap_b32_e32 v8, v4
	v_permlane16_swap_b32_e32 v9, v5
	v_xor_b32_e32 v232, 16, v242
	v_lshlrev_b32_e32 v232, 2, v232
	v_xor_b32_e32 v233, 32, v242
	v_lshlrev_b32_e32 v233, 2, v233
	s_waitcnt vmcnt(15)
	ds_write_b128 v234, v[144:147]
	ds_read_b128 v[144:147], v235
	s_waitcnt vmcnt(14)
	ds_write_b128 v234, v[148:151]
	ds_read_b128 v[148:151], v235
	s_waitcnt lgkmcnt(2)
	v_lshlrev_b32_e32 v140, 16, v144
	v_and_b32_e32 v141, 0xffff0000, v144
	v_lshlrev_b32_e32 v142, 16, v145
	v_and_b32_e32 v143, 0xffff0000, v145
	v_pk_add_f32 v[126:127], v[126:127], v[140:141]
	v_pk_add_f32 v[128:129], v[128:129], v[142:143]
	v_lshlrev_b32_e32 v140, 16, v146
	v_and_b32_e32 v141, 0xffff0000, v146
	v_lshlrev_b32_e32 v142, 16, v147
	v_and_b32_e32 v143, 0xffff0000, v147
	v_pk_add_f32 v[122:123], v[122:123], v[140:141]
	v_pk_add_f32 v[124:125], v[124:125], v[142:143]
	v_cvt_pk_bf16_f32 v144, v126, v127
	v_cvt_pk_bf16_f32 v145, v128, v129
	v_cvt_pk_bf16_f32 v146, v122, v123
	v_cvt_pk_bf16_f32 v147, v124, v125
	ds_write_b128 v235, v[144:147]
	ds_read_b128 v[144:147], v234
	s_waitcnt vmcnt(13)
; __device__ __forceinline__ unsigned cvt_pk_bf16(float lo, float hi) { f32x2_t v = {lo, hi}; bf16x2_t b = __builtin_convertvector(v, bf16x2_t); return __builtin_bit_cast(unsigned, b); }
;     __device__ __forceinline__ void operator()(const f32x4 (&acc)[2][2][4][2], const Unit& u, int wr, int wc, int fr, int fq) const {
;     ...
;         for (int ai = 0; ai < 2; ++ai)
; #pragma unroll
;             for (int m = 0; m < 4; ++m) { const int row = row0 + ai * HALF + m * 16; const size_t off = (size_t)row * 1024 + col0; float q = 0.f;
; #pragma unroll
;                 for (int bj = 0; bj < 2; ++bj)
; #pragma unroll
;                     for (int n = 0; n < 2; ++n) { const size_t o2 = off + bj * HALF + n * 16; const u32x2v b = bs[ai][m][bj][n];
;                         const f32x4 bf = {__builtin_bit_cast(float, b.x << 16), __builtin_bit_cast(float, b.x & 0xffff0000u), __builtin_bit_cast(float, b.y << 16), __builtin_bit_cast(float, b.y & 0xffff0000u)};
;                         const f32x4 o = bf + acc[ai][bj][m][n];
;                         u32x2v w; w.x = cvt_pk_bf16(o[0], o[1]); w.y = cvt_pk_bf16(o[2], o[3]); *(u32x2v*)(hb + o2) = w;
;                         q += (o[0] * o[0] + o[1] * o[1]) + (o[2] * o[2] + o[3] * o[3]); }
	ds_write_b128 v234, v[152:155]
	ds_read_b128 v[152:155], v235
	v_mul_f32_e32 v140, v126, v126
	v_mul_f32_e32 v141, v122, v122
	v_fmac_f32_e32 v140, v127, v127
	v_fmac_f32_e32 v141, v123, v123
	v_fmac_f32_e32 v140, v128, v128
	v_fmac_f32_e32 v141, v124, v124
	v_fmac_f32_e32 v140, v129, v129
	v_fmac_f32_e32 v141, v125, v125
	v_add_f32_e32 v138, v140, v141
	s_waitcnt lgkmcnt(2)
	global_store_dwordx4 v[212:213], v[144:147], off
	v_lshlrev_b32_e32 v140, 16, v148
	v_and_b32_e32 v141, 0xffff0000, v148
	v_lshlrev_b32_e32 v142, 16, v149
	v_and_b32_e32 v143, 0xffff0000, v149
	v_pk_add_f32 v[118:119], v[118:119], v[140:141]
	v_pk_add_f32 v[120:121], v[120:121], v[142:143]
	v_lshlrev_b32_e32 v140, 16, v150
	v_and_b32_e32 v141, 0xffff0000, v150
	v_lshlrev_b32_e32 v142, 16, v151
	v_and_b32_e32 v143, 0xffff0000, v151
	v_pk_add_f32 v[114:115], v[114:115], v[140:141]
	v_pk_add_f32 v[116:117], v[116:117], v[142:143]
	v_cvt_pk_bf16_f32 v148, v118, v119
	v_cvt_pk_bf16_f32 v149, v120, v121
	v_cvt_pk_bf16_f32 v150, v114, v115
	v_cvt_pk_bf16_f32 v151, v116, v117
	ds_write_b128 v235, v[148:151]
	ds_read_b128 v[148:151], v234
	s_waitcnt vmcnt(13)
	ds_write_b128 v234, v[156:159]
	ds_read_b128 v[156:159], v235
	v_mul_f32_e32 v140, v118, v118
	v_mul_f32_e32 v141, v114, v114
	v_fmac_f32_e32 v140, v119, v119
	v_fmac_f32_e32 v141, v115, v115
	v_fmac_f32_e32 v140, v120, v120
	v_fmac_f32_e32 v141, v116, v116
	v_fmac_f32_e32 v140, v121, v121
	v_fmac_f32_e32 v141, v117, v117
	v_add_f32_e32 v139, v140, v141
	v_add_f32_e32 v126, v138, v139
	s_waitcnt lgkmcnt(2)
	global_store_dwordx4 v[212:213], v[148:151], off offset:256
	v_lshlrev_b32_e32 v140, 16, v152
	v_and_b32_e32 v141, 0xffff0000, v152
	v_lshlrev_b32_e32 v142, 16, v153
	v_and_b32_e32 v143, 0xffff0000, v153
	v_pk_add_f32 v[110:111], v[110:111], v[140:141]
	v_pk_add_f32 v[112:113], v[112:113], v[142:143]
	v_lshlrev_b32_e32 v140, 16, v154
	v_and_b32_e32 v141, 0xffff0000, v154
	v_lshlrev_b32_e32 v142, 16, v155
	v_and_b32_e32 v143, 0xffff0000, v155
	v_pk_add_f32 v[106:107], v[106:107], v[140:141]
	v_pk_add_f32 v[108:109], v[108:109], v[142:143]
	v_cvt_pk_bf16_f32 v152, v110, v111
	v_cvt_pk_bf16_f32 v153, v112, v113
	v_cvt_pk_bf16_f32 v154, v106, v107
	v_cvt_pk_bf16_f32 v155, v108, v109
	ds_write_b128 v235, v[152:155]
	ds_read_b128 v[152:155], v234
	s_waitcnt vmcnt(13)
	ds_write_b128 v234, v[160:163]
	ds_read_b128 v[160:163], v235
	v_mul_f32_e32 v140, v110, v110
	v_mul_f32_e32 v141, v106, v106
	v_fmac_f32_e32 v140, v111, v111
	v_fmac_f32_e32 v141, v107, v107
	v_fmac_f32_e32 v140, v112, v112
	v_fmac_f32_e32 v141, v108, v108
	v_fmac_f32_e32 v140, v113, v113
	v_fmac_f32_e32 v141, v109, v109
	v_add_f32_e32 v138, v140, v141
	s_waitcnt lgkmcnt(2)
	global_store_dwordx4 v[214:215], v[152:155], off
	v_lshlrev_b32_e32 v140, 16, v156
	v_and_b32_e32 v141, 0xffff0000, v156
	v_lshlrev_b32_e32 v142, 16, v157
	v_and_b32_e32 v143, 0xffff0000, v157
	v_pk_add_f32 v[102:103], v[102:103], v[140:141]
	v_pk_add_f32 v[104:105], v[104:105], v[142:143]
	v_lshlrev_b32_e32 v140, 16, v158
	v_and_b32_e32 v141, 0xffff0000, v158
	v_lshlrev_b32_e32 v142, 16, v159
	v_and_b32_e32 v143, 0xffff0000, v159
	v_pk_add_f32 v[98:99], v[98:99], v[140:141]
	v_pk_add_f32 v[100:101], v[100:101], v[142:143]
	v_cvt_pk_bf16_f32 v156, v102, v103
	v_cvt_pk_bf16_f32 v157, v104, v105
	v_cvt_pk_bf16_f32 v158, v98, v99
	v_cvt_pk_bf16_f32 v159, v100, v101
	ds_write_b128 v235, v[156:159]
	ds_read_b128 v[156:159], v234
	s_waitcnt vmcnt(13)
	ds_write_b128 v234, v[168:171]
	ds_read_b128 v[168:171], v235
	v_mul_f32_e32 v140, v102, v102
	v_mul_f32_e32 v141, v98, v98
	v_fmac_f32_e32 v140, v103, v103
	v_fmac_f32_e32 v141, v99, v99
	v_fmac_f32_e32 v140, v104, v104
	v_fmac_f32_e32 v141, v100, v100
	v_fmac_f32_e32 v140, v105, v105
	v_fmac_f32_e32 v141, v101, v101
	v_add_f32_e32 v139, v140, v141
	v_add_f32_e32 v110, v138, v139
	s_waitcnt lgkmcnt(2)
	global_store_dwordx4 v[214:215], v[156:159], off offset:256
	v_lshlrev_b32_e32 v140, 16, v160
	v_and_b32_e32 v141, 0xffff0000, v160
	v_lshlrev_b32_e32 v142, 16, v161
	v_and_b32_e32 v143, 0xffff0000, v161
	v_pk_add_f32 v[94:95], v[94:95], v[140:141]
	v_pk_add_f32 v[96:97], v[96:97], v[142:143]
	v_lshlrev_b32_e32 v140, 16, v162
	v_and_b32_e32 v141, 0xffff0000, v162
	v_lshlrev_b32_e32 v142, 16, v163
	v_and_b32_e32 v143, 0xffff0000, v163
	v_pk_add_f32 v[90:91], v[90:91], v[140:141]
	v_pk_add_f32 v[92:93], v[92:93], v[142:143]
	v_cvt_pk_bf16_f32 v160, v94, v95
	v_cvt_pk_bf16_f32 v161, v96, v97
	v_cvt_pk_bf16_f32 v162, v90, v91
	v_cvt_pk_bf16_f32 v163, v92, v93
	ds_write_b128 v235, v[160:163]
	ds_read_b128 v[160:163], v234
	s_waitcnt vmcnt(13)
	ds_write_b128 v234, v[172:175]
	ds_read_b128 v[172:175], v235
	v_mul_f32_e32 v140, v94, v94
	v_mul_f32_e32 v141, v90, v90
	v_fmac_f32_e32 v140, v95, v95
	v_fmac_f32_e32 v141, v91, v91
	v_fmac_f32_e32 v140, v96, v96
	v_fmac_f32_e32 v141, v92, v92
	v_fmac_f32_e32 v140, v97, v97
	v_fmac_f32_e32 v141, v93, v93
	v_add_f32_e32 v138, v140, v141
	s_waitcnt lgkmcnt(2)
	global_store_dwordx4 v[216:217], v[160:163], off
	v_lshlrev_b32_e32 v140, 16, v168
	v_and_b32_e32 v141, 0xffff0000, v168
	v_lshlrev_b32_e32 v142, 16, v169
	v_and_b32_e32 v143, 0xffff0000, v169
	v_pk_add_f32 v[86:87], v[86:87], v[140:141]
	v_pk_add_f32 v[88:89], v[88:89], v[142:143]
	v_lshlrev_b32_e32 v140, 16, v170
	v_and_b32_e32 v141, 0xffff0000, v170
	v_lshlrev_b32_e32 v142, 16, v171
	v_and_b32_e32 v143, 0xffff0000, v171
	v_pk_add_f32 v[82:83], v[82:83], v[140:141]
	v_pk_add_f32 v[84:85], v[84:85], v[142:143]
	v_cvt_pk_bf16_f32 v168, v86, v87
	v_cvt_pk_bf16_f32 v169, v88, v89
	v_cvt_pk_bf16_f32 v170, v82, v83
	v_cvt_pk_bf16_f32 v171, v84, v85
	ds_write_b128 v235, v[168:171]
	ds_read_b128 v[168:171], v234
	s_waitcnt vmcnt(13)
; __device__ __forceinline__ unsigned cvt_pk_bf16(float lo, float hi) { f32x2_t v = {lo, hi}; bf16x2_t b = __builtin_convertvector(v, bf16x2_t); return __builtin_bit_cast(unsigned, b); }
;     __device__ __forceinline__ void operator()(const f32x4 (&acc)[2][2][4][2], const Unit& u, int wr, int wc, int fr, int fq) const {
;     ...
;         for (int ai = 0; ai < 2; ++ai)
; #pragma unroll
;             for (int m = 0; m < 4; ++m) { const int row = row0 + ai * HALF + m * 16; const size_t off = (size_t)row * 1024 + col0; float q = 0.f;
; #pragma unroll
;                 for (int bj = 0; bj < 2; ++bj)
; #pragma unroll
;                     for (int n = 0; n < 2; ++n) { const size_t o2 = off + bj * HALF + n * 16; const u32x2v b = bs[ai][m][bj][n];
;                         const f32x4 bf = {__builtin_bit_cast(float, b.x << 16), __builtin_bit_cast(float, b.x & 0xffff0000u), __builtin_bit_cast(float, b.y << 16), __builtin_bit_cast(float, b.y & 0xffff0000u)};
;                         const f32x4 o = bf + acc[ai][bj][m][n];
;                         u32x2v w; w.x = cvt_pk_bf16(o[0], o[1]); w.y = cvt_pk_bf16(o[2], o[3]); *(u32x2v*)(hb + o2) = w;
;                         q += (o[0] * o[0] + o[1] * o[1]) + (o[2] * o[2] + o[3] * o[3]); }
	ds_write_b128 v234, v[176:179]
	ds_read_b128 v[176:179], v235
	v_mul_f32_e32 v140, v86, v86
	v_mul_f32_e32 v141, v82, v82
	v_fmac_f32_e32 v140, v87, v87
	v_fmac_f32_e32 v141, v83, v83
	v_fmac_f32_e32 v140, v88, v88
	v_fmac_f32_e32 v141, v84, v84
	v_fmac_f32_e32 v140, v89, v89
	v_fmac_f32_e32 v141, v85, v85
	v_add_f32_e32 v139, v140, v141
	v_add_f32_e32 v94, v138, v139
	s_waitcnt lgkmcnt(2)
	global_store_dwordx4 v[216:217], v[168:171], off offset:256
	v_lshlrev_b32_e32 v140, 16, v172
	v_and_b32_e32 v141, 0xffff0000, v172
	v_lshlrev_b32_e32 v142, 16, v173
	v_and_b32_e32 v143, 0xffff0000, v173
	v_pk_add_f32 v[78:79], v[78:79], v[140:141]
	v_pk_add_f32 v[80:81], v[80:81], v[142:143]
	v_lshlrev_b32_e32 v140, 16, v174
	v_and_b32_e32 v141, 0xffff0000, v174
	v_lshlrev_b32_e32 v142, 16, v175
	v_and_b32_e32 v143, 0xffff0000, v175
	v_pk_add_f32 v[74:75], v[74:75], v[140:141]
	v_pk_add_f32 v[76:77], v[76:77], v[142:143]
	v_cvt_pk_bf16_f32 v172, v78, v79
	v_cvt_pk_bf16_f32 v173, v80, v81
	v_cvt_pk_bf16_f32 v174, v74, v75
	v_cvt_pk_bf16_f32 v175, v76, v77
	ds_write_b128 v235, v[172:175]
	ds_read_b128 v[172:175], v234
	s_waitcnt vmcnt(13)
	ds_write_b128 v234, v[180:183]
	ds_read_b128 v[180:183], v235
	v_mul_f32_e32 v140, v78, v78
	v_mul_f32_e32 v141, v74, v74
	v_fmac_f32_e32 v140, v79, v79
	v_fmac_f32_e32 v141, v75, v75
	v_fmac_f32_e32 v140, v80, v80
	v_fmac_f32_e32 v141, v76, v76
	v_fmac_f32_e32 v140, v81, v81
	v_fmac_f32_e32 v141, v77, v77
	v_add_f32_e32 v138, v140, v141
	s_waitcnt lgkmcnt(2)
	global_store_dwordx4 v[218:219], v[172:175], off
	v_lshlrev_b32_e32 v140, 16, v176
	v_and_b32_e32 v141, 0xffff0000, v176
	v_lshlrev_b32_e32 v142, 16, v177
	v_and_b32_e32 v143, 0xffff0000, v177
	v_pk_add_f32 v[70:71], v[70:71], v[140:141]
	v_pk_add_f32 v[72:73], v[72:73], v[142:143]
	v_lshlrev_b32_e32 v140, 16, v178
	v_and_b32_e32 v141, 0xffff0000, v178
	v_lshlrev_b32_e32 v142, 16, v179
	v_and_b32_e32 v143, 0xffff0000, v179
	v_pk_add_f32 v[66:67], v[66:67], v[140:141]
	v_pk_add_f32 v[68:69], v[68:69], v[142:143]
	v_cvt_pk_bf16_f32 v176, v70, v71
	v_cvt_pk_bf16_f32 v177, v72, v73
	v_cvt_pk_bf16_f32 v178, v66, v67
	v_cvt_pk_bf16_f32 v179, v68, v69
	ds_write_b128 v235, v[176:179]
	ds_read_b128 v[176:179], v234
	s_waitcnt vmcnt(13)
	ds_write_b128 v234, v[184:187]
	ds_read_b128 v[184:187], v235
	v_mul_f32_e32 v140, v70, v70
	v_mul_f32_e32 v141, v66, v66
	v_fmac_f32_e32 v140, v71, v71
	v_fmac_f32_e32 v141, v67, v67
	v_fmac_f32_e32 v140, v72, v72
	v_fmac_f32_e32 v141, v68, v68
	v_fmac_f32_e32 v140, v73, v73
	v_fmac_f32_e32 v141, v69, v69
	v_add_f32_e32 v139, v140, v141
	v_add_f32_e32 v78, v138, v139
	s_waitcnt lgkmcnt(2)
	global_store_dwordx4 v[218:219], v[176:179], off offset:256
	v_lshlrev_b32_e32 v140, 16, v180
	v_and_b32_e32 v141, 0xffff0000, v180
	v_lshlrev_b32_e32 v142, 16, v181
	v_and_b32_e32 v143, 0xffff0000, v181
	v_pk_add_f32 v[62:63], v[62:63], v[140:141]
	v_pk_add_f32 v[64:65], v[64:65], v[142:143]
	v_lshlrev_b32_e32 v140, 16, v182
	v_and_b32_e32 v141, 0xffff0000, v182
	v_lshlrev_b32_e32 v142, 16, v183
	v_and_b32_e32 v143, 0xffff0000, v183
	v_pk_add_f32 v[58:59], v[58:59], v[140:141]
	v_pk_add_f32 v[60:61], v[60:61], v[142:143]
	v_cvt_pk_bf16_f32 v180, v62, v63
	v_cvt_pk_bf16_f32 v181, v64, v65
	v_cvt_pk_bf16_f32 v182, v58, v59
	v_cvt_pk_bf16_f32 v183, v60, v61
	ds_write_b128 v235, v[180:183]
	ds_read_b128 v[180:183], v234
	s_waitcnt vmcnt(13)
	ds_write_b128 v234, v[188:191]
	ds_read_b128 v[188:191], v235
	v_mul_f32_e32 v140, v62, v62
	v_mul_f32_e32 v141, v58, v58
	v_fmac_f32_e32 v140, v63, v63
	v_fmac_f32_e32 v141, v59, v59
	v_fmac_f32_e32 v140, v64, v64
	v_fmac_f32_e32 v141, v60, v60
	v_fmac_f32_e32 v140, v65, v65
	v_fmac_f32_e32 v141, v61, v61
	v_add_f32_e32 v138, v140, v141
	s_waitcnt lgkmcnt(2)
	global_store_dwordx4 v[220:221], v[180:183], off
	v_lshlrev_b32_e32 v140, 16, v184
	v_and_b32_e32 v141, 0xffff0000, v184
	v_lshlrev_b32_e32 v142, 16, v185
	v_and_b32_e32 v143, 0xffff0000, v185
	v_pk_add_f32 v[54:55], v[54:55], v[140:141]
	v_pk_add_f32 v[56:57], v[56:57], v[142:143]
	v_lshlrev_b32_e32 v140, 16, v186
	v_and_b32_e32 v141, 0xffff0000, v186
	v_lshlrev_b32_e32 v142, 16, v187
	v_and_b32_e32 v143, 0xffff0000, v187
	v_pk_add_f32 v[50:51], v[50:51], v[140:141]
	v_pk_add_f32 v[52:53], v[52:53], v[142:143]
	v_cvt_pk_bf16_f32 v184, v54, v55
	v_cvt_pk_bf16_f32 v185, v56, v57
	v_cvt_pk_bf16_f32 v186, v50, v51
	v_cvt_pk_bf16_f32 v187, v52, v53
	ds_write_b128 v235, v[184:187]
	ds_read_b128 v[184:187], v234
	s_waitcnt vmcnt(13)
	ds_write_b128 v234, v[192:195]
	ds_read_b128 v[192:195], v235
	v_mul_f32_e32 v140, v54, v54
	v_mul_f32_e32 v141, v50, v50
	v_fmac_f32_e32 v140, v55, v55
	v_fmac_f32_e32 v141, v51, v51
	v_fmac_f32_e32 v140, v56, v56
	v_fmac_f32_e32 v141, v52, v52
	v_fmac_f32_e32 v140, v57, v57
	v_fmac_f32_e32 v141, v53, v53
	v_add_f32_e32 v139, v140, v141
	v_add_f32_e32 v62, v138, v139
	s_waitcnt lgkmcnt(2)
	global_store_dwordx4 v[220:221], v[184:187], off offset:256
	v_lshlrev_b32_e32 v140, 16, v188
	v_and_b32_e32 v141, 0xffff0000, v188
	v_lshlrev_b32_e32 v142, 16, v189
	v_and_b32_e32 v143, 0xffff0000, v189
	v_pk_add_f32 v[46:47], v[46:47], v[140:141]
	v_pk_add_f32 v[48:49], v[48:49], v[142:143]
	v_lshlrev_b32_e32 v140, 16, v190
	v_and_b32_e32 v141, 0xffff0000, v190
	v_lshlrev_b32_e32 v142, 16, v191
	v_and_b32_e32 v143, 0xffff0000, v191
	v_pk_add_f32 v[42:43], v[42:43], v[140:141]
	v_pk_add_f32 v[44:45], v[44:45], v[142:143]
	v_cvt_pk_bf16_f32 v188, v46, v47
	v_cvt_pk_bf16_f32 v189, v48, v49
	v_cvt_pk_bf16_f32 v190, v42, v43
	v_cvt_pk_bf16_f32 v191, v44, v45
	ds_write_b128 v235, v[188:191]
	ds_read_b128 v[188:191], v234
	s_waitcnt vmcnt(13)
; __device__ __forceinline__ unsigned cvt_pk_bf16(float lo, float hi) { f32x2_t v = {lo, hi}; bf16x2_t b = __builtin_convertvector(v, bf16x2_t); return __builtin_bit_cast(unsigned, b); }
;     __device__ __forceinline__ void operator()(const f32x4 (&acc)[2][2][4][2], const Unit& u, int wr, int wc, int fr, int fq) const {
;     ...
;         for (int ai = 0; ai < 2; ++ai)
; #pragma unroll
;             for (int m = 0; m < 4; ++m) { const int row = row0 + ai * HALF + m * 16; const size_t off = (size_t)row * 1024 + col0; float q = 0.f;
; #pragma unroll
;                 for (int bj = 0; bj < 2; ++bj)
; #pragma unroll
;                     for (int n = 0; n < 2; ++n) { const size_t o2 = off + bj * HALF + n * 16; const u32x2v b = bs[ai][m][bj][n];
;                         const f32x4 bf = {__builtin_bit_cast(float, b.x << 16), __builtin_bit_cast(float, b.x & 0xffff0000u), __builtin_bit_cast(float, b.y << 16), __builtin_bit_cast(float, b.y & 0xffff0000u)};
;                         const f32x4 o = bf + acc[ai][bj][m][n];
;                         u32x2v w; w.x = cvt_pk_bf16(o[0], o[1]); w.y = cvt_pk_bf16(o[2], o[3]); *(u32x2v*)(hb + o2) = w;
;                         q += (o[0] * o[0] + o[1] * o[1]) + (o[2] * o[2] + o[3] * o[3]); }
	ds_write_b128 v234, v[196:199]
	ds_read_b128 v[196:199], v235
	v_mul_f32_e32 v140, v46, v46
	v_mul_f32_e32 v141, v42, v42
	v_fmac_f32_e32 v140, v47, v47
	v_fmac_f32_e32 v141, v43, v43
	v_fmac_f32_e32 v140, v48, v48
	v_fmac_f32_e32 v141, v44, v44
	v_fmac_f32_e32 v140, v49, v49
	v_fmac_f32_e32 v141, v45, v45
	v_add_f32_e32 v138, v140, v141
	s_waitcnt lgkmcnt(2)
	global_store_dwordx4 v[222:223], v[188:191], off
	v_lshlrev_b32_e32 v140, 16, v192
	v_and_b32_e32 v141, 0xffff0000, v192
	v_lshlrev_b32_e32 v142, 16, v193
	v_and_b32_e32 v143, 0xffff0000, v193
	v_pk_add_f32 v[38:39], v[38:39], v[140:141]
	v_pk_add_f32 v[40:41], v[40:41], v[142:143]
	v_lshlrev_b32_e32 v140, 16, v194
	v_and_b32_e32 v141, 0xffff0000, v194
	v_lshlrev_b32_e32 v142, 16, v195
	v_and_b32_e32 v143, 0xffff0000, v195
	v_pk_add_f32 v[34:35], v[34:35], v[140:141]
	v_pk_add_f32 v[36:37], v[36:37], v[142:143]
	v_cvt_pk_bf16_f32 v192, v38, v39
	v_cvt_pk_bf16_f32 v193, v40, v41
	v_cvt_pk_bf16_f32 v194, v34, v35
	v_cvt_pk_bf16_f32 v195, v36, v37
	ds_write_b128 v235, v[192:195]
	ds_read_b128 v[192:195], v234
	s_waitcnt vmcnt(13)
	ds_write_b128 v234, v[200:203]
	ds_read_b128 v[200:203], v235
	v_mul_f32_e32 v140, v38, v38
	v_mul_f32_e32 v141, v34, v34
	v_fmac_f32_e32 v140, v39, v39
	v_fmac_f32_e32 v141, v35, v35
	v_fmac_f32_e32 v140, v40, v40
	v_fmac_f32_e32 v141, v36, v36
	v_fmac_f32_e32 v140, v41, v41
	v_fmac_f32_e32 v141, v37, v37
	v_add_f32_e32 v139, v140, v141
	v_add_f32_e32 v46, v138, v139
	s_waitcnt lgkmcnt(2)
	global_store_dwordx4 v[222:223], v[192:195], off offset:256
	v_lshlrev_b32_e32 v140, 16, v196
	v_and_b32_e32 v141, 0xffff0000, v196
	v_lshlrev_b32_e32 v142, 16, v197
	v_and_b32_e32 v143, 0xffff0000, v197
	v_pk_add_f32 v[30:31], v[30:31], v[140:141]
	v_pk_add_f32 v[32:33], v[32:33], v[142:143]
	v_lshlrev_b32_e32 v140, 16, v198
	v_and_b32_e32 v141, 0xffff0000, v198
	v_lshlrev_b32_e32 v142, 16, v199
	v_and_b32_e32 v143, 0xffff0000, v199
	v_pk_add_f32 v[26:27], v[26:27], v[140:141]
	v_pk_add_f32 v[28:29], v[28:29], v[142:143]
	v_cvt_pk_bf16_f32 v196, v30, v31
	v_cvt_pk_bf16_f32 v197, v32, v33
	v_cvt_pk_bf16_f32 v198, v26, v27
	v_cvt_pk_bf16_f32 v199, v28, v29
	ds_write_b128 v235, v[196:199]
	ds_read_b128 v[196:199], v234
	s_waitcnt vmcnt(13)
	ds_write_b128 v234, v[204:207]
	ds_read_b128 v[204:207], v235
	v_mul_f32_e32 v140, v30, v30
	v_mul_f32_e32 v141, v26, v26
	v_fmac_f32_e32 v140, v31, v31
	v_fmac_f32_e32 v141, v27, v27
	v_fmac_f32_e32 v140, v32, v32
	v_fmac_f32_e32 v141, v28, v28
	v_fmac_f32_e32 v140, v33, v33
	v_fmac_f32_e32 v141, v29, v29
	v_add_f32_e32 v138, v140, v141
	s_waitcnt lgkmcnt(2)
	global_store_dwordx4 v[224:225], v[196:199], off
	v_lshlrev_b32_e32 v140, 16, v200
	v_and_b32_e32 v141, 0xffff0000, v200
	v_lshlrev_b32_e32 v142, 16, v201
	v_and_b32_e32 v143, 0xffff0000, v201
	v_pk_add_f32 v[22:23], v[22:23], v[140:141]
	v_pk_add_f32 v[24:25], v[24:25], v[142:143]
	v_lshlrev_b32_e32 v140, 16, v202
	v_and_b32_e32 v141, 0xffff0000, v202
	v_lshlrev_b32_e32 v142, 16, v203
	v_and_b32_e32 v143, 0xffff0000, v203
	v_pk_add_f32 v[18:19], v[18:19], v[140:141]
	v_pk_add_f32 v[20:21], v[20:21], v[142:143]
	v_cvt_pk_bf16_f32 v200, v22, v23
	v_cvt_pk_bf16_f32 v201, v24, v25
	v_cvt_pk_bf16_f32 v202, v18, v19
	v_cvt_pk_bf16_f32 v203, v20, v21
	ds_write_b128 v235, v[200:203]
	ds_read_b128 v[200:203], v234
	s_waitcnt vmcnt(13)
	ds_write_b128 v234, v[208:211]
	ds_read_b128 v[208:211], v235
	v_mul_f32_e32 v140, v22, v22
	v_mul_f32_e32 v141, v18, v18
	v_fmac_f32_e32 v140, v23, v23
	v_fmac_f32_e32 v141, v19, v19
	v_fmac_f32_e32 v140, v24, v24
	v_fmac_f32_e32 v141, v20, v20
	v_fmac_f32_e32 v140, v25, v25
	v_fmac_f32_e32 v141, v21, v21
	v_add_f32_e32 v139, v140, v141
	v_add_f32_e32 v30, v138, v139
	s_waitcnt lgkmcnt(2)
; __device__ __forceinline__ unsigned cvt_pk_bf16(float lo, float hi) { f32x2_t v = {lo, hi}; bf16x2_t b = __builtin_convertvector(v, bf16x2_t); return __builtin_bit_cast(unsigned, b); }
;     __device__ __forceinline__ void operator()(const f32x4 (&acc)[2][2][4][2], const Unit& u, int wr, int wc, int fr, int fq) const {
;     ...
;         for (int ai = 0; ai < 2; ++ai)
; #pragma unroll
;             for (int m = 0; m < 4; ++m) { const int row = row0 + ai * HALF + m * 16; const size_t off = (size_t)row * 1024 + col0; float q = 0.f;
; #pragma unroll
;                 for (int bj = 0; bj < 2; ++bj)
; #pragma unroll
;                     for (int n = 0; n < 2; ++n) { const size_t o2 = off + bj * HALF + n * 16; const u32x2v b = bs[ai][m][bj][n];
;                         const f32x4 bf = {__builtin_bit_cast(float, b.x << 16), __builtin_bit_cast(float, b.x & 0xffff0000u), __builtin_bit_cast(float, b.y << 16), __builtin_bit_cast(float, b.y & 0xffff0000u)};
;                         const f32x4 o = bf + acc[ai][bj][m][n];
;                         u32x2v w; w.x = cvt_pk_bf16(o[0], o[1]); w.y = cvt_pk_bf16(o[2], o[3]); *(u32x2v*)(hb + o2) = w;
;                         q += (o[0] * o[0] + o[1] * o[1]) + (o[2] * o[2] + o[3] * o[3]); }
;                 q += __shfl_xor(q, 16); q += __shfl_xor(q, 32);
;                 if (fq == 0) ssq[(size_t)(4 * u.pn + wc) * 16384 + row] = q; }
	global_store_dwordx4 v[224:225], v[200:203], off offset:256
	v_lshlrev_b32_e32 v140, 16, v204
	v_and_b32_e32 v141, 0xffff0000, v204
	v_lshlrev_b32_e32 v142, 16, v205
	v_and_b32_e32 v143, 0xffff0000, v205
	v_pk_add_f32 v[14:15], v[14:15], v[140:141]
	v_pk_add_f32 v[16:17], v[16:17], v[142:143]
	v_lshlrev_b32_e32 v140, 16, v206
	v_and_b32_e32 v141, 0xffff0000, v206
	v_lshlrev_b32_e32 v142, 16, v207
	v_and_b32_e32 v143, 0xffff0000, v207
	v_pk_add_f32 v[10:11], v[10:11], v[140:141]
	v_pk_add_f32 v[12:13], v[12:13], v[142:143]
	v_cvt_pk_bf16_f32 v204, v14, v15
	v_cvt_pk_bf16_f32 v205, v16, v17
	v_cvt_pk_bf16_f32 v206, v10, v11
	v_cvt_pk_bf16_f32 v207, v12, v13
	ds_write_b128 v235, v[204:207]
	ds_read_b128 v[204:207], v234
	v_mul_f32_e32 v140, v14, v14
	v_mul_f32_e32 v141, v10, v10
	v_fmac_f32_e32 v140, v15, v15
	v_fmac_f32_e32 v141, v11, v11
	v_fmac_f32_e32 v140, v16, v16
	v_fmac_f32_e32 v141, v12, v12
	v_fmac_f32_e32 v140, v17, v17
	v_fmac_f32_e32 v141, v13, v13
	v_add_f32_e32 v138, v140, v141
	s_waitcnt lgkmcnt(0)
	global_store_dwordx4 v[226:227], v[204:207], off
	v_lshlrev_b32_e32 v140, 16, v208
	v_and_b32_e32 v141, 0xffff0000, v208
	v_lshlrev_b32_e32 v142, 16, v209
	v_and_b32_e32 v143, 0xffff0000, v209
	v_pk_add_f32 v[6:7], v[6:7], v[140:141]
	v_pk_add_f32 v[8:9], v[8:9], v[142:143]
	v_lshlrev_b32_e32 v140, 16, v210
	v_and_b32_e32 v141, 0xffff0000, v210
	v_lshlrev_b32_e32 v142, 16, v211
	v_and_b32_e32 v143, 0xffff0000, v211
	v_pk_add_f32 v[2:3], v[2:3], v[140:141]
	v_pk_add_f32 v[4:5], v[4:5], v[142:143]
	v_cvt_pk_bf16_f32 v208, v6, v7
	v_cvt_pk_bf16_f32 v209, v8, v9
	v_cvt_pk_bf16_f32 v210, v2, v3
	v_cvt_pk_bf16_f32 v211, v4, v5
	ds_write_b128 v235, v[208:211]
	ds_read_b128 v[208:211], v234
	v_mul_f32_e32 v140, v6, v6
	v_mul_f32_e32 v141, v2, v2
	v_fmac_f32_e32 v140, v7, v7
	v_fmac_f32_e32 v141, v3, v3
	v_fmac_f32_e32 v140, v8, v8
	v_fmac_f32_e32 v141, v4, v4
	v_fmac_f32_e32 v140, v9, v9
	v_fmac_f32_e32 v141, v5, v5
	v_add_f32_e32 v139, v140, v141
	v_add_f32_e32 v14, v138, v139
	s_waitcnt lgkmcnt(0)
	global_store_dwordx4 v[226:227], v[208:211], off offset:256
	ds_bpermute_b32 v127, v232, v126
	ds_bpermute_b32 v111, v232, v110
	ds_bpermute_b32 v95, v232, v94
	ds_bpermute_b32 v79, v232, v78
	ds_bpermute_b32 v63, v232, v62
	ds_bpermute_b32 v47, v232, v46
	ds_bpermute_b32 v31, v232, v30
	ds_bpermute_b32 v15, v232, v14
	s_waitcnt lgkmcnt(0)
	v_add_f32_e32 v126, v126, v127
	v_add_f32_e32 v110, v110, v111
	v_add_f32_e32 v94, v94, v95
	v_add_f32_e32 v78, v78, v79
	v_add_f32_e32 v62, v62, v63
	v_add_f32_e32 v46, v46, v47
	v_add_f32_e32 v30, v30, v31
	v_add_f32_e32 v14, v14, v15
	ds_bpermute_b32 v127, v233, v126
	ds_bpermute_b32 v111, v233, v110
	ds_bpermute_b32 v95, v233, v94
	ds_bpermute_b32 v79, v233, v78
	ds_bpermute_b32 v63, v233, v62
	ds_bpermute_b32 v47, v233, v46
	ds_bpermute_b32 v31, v233, v30
	ds_bpermute_b32 v15, v233, v14
	s_waitcnt lgkmcnt(0)
	v_add_f32_e32 v126, v126, v127
	v_add_f32_e32 v110, v110, v111
	v_add_f32_e32 v94, v94, v95
	v_add_f32_e32 v78, v78, v79
	v_add_f32_e32 v62, v62, v63
	v_add_f32_e32 v46, v46, v47
	v_add_f32_e32 v30, v30, v31
	v_add_f32_e32 v14, v14, v15
	s_lshl_b32 s6, s23, 2
	s_or_b32 s6, s6, s12
	s_ashr_i32 s7, s6, 31
	s_lshl_b64 s[6:7], s[6:7], 16
	v_readlane_b32 s10, v252, 15
	v_readlane_b32 s11, v252, 16
	s_add_u32 s10, s10, s6
	s_addc_u32 s11, s11, s7
	s_lshl_b32 s6, s24, 8
	s_add_i32 s6, s6, s16
	v_add_u32_e32 v136, s6, v228
	v_ashrrev_i32_e32 v137, 31, v136
	v_lshl_add_u64 v[140:141], v[136:137], 2, s[10:11]
	s_and_saveexec_b64 s[8:9], s[38:39]
	global_store_dword v[140:141], v126, off
	global_store_dword v[140:141], v110, off offset:64
	global_store_dword v[140:141], v94, off offset:128
	global_store_dword v[140:141], v78, off offset:192
	global_store_dword v[140:141], v62, off offset:512
	global_store_dword v[140:141], v46, off offset:576
	global_store_dword v[140:141], v30, off offset:640
	global_store_dword v[140:141], v14, off offset:704
